# grid barrier: cache invalidate issued at arrival (overlapped with the arrival atomic) instead of after the release
# speedup vs baseline: 1.0545x; 1.0117x over previous
.LBB0_250:
	s_or_b64 exec, exec, s[12:13]
	s_waitcnt vmcnt(0)
	global_atomic_add v[188:189], v193, off
	s_waitcnt vmcnt(0)

.LBB0_499:
	buffer_inv sc1
	global_atomic_add v3, v[186:187], v193, off sc0
	v_cvt_f32_u32_e32 v1, v2
	v_sub_u32_e32 v4, 0, v2
	v_rcp_iflag_f32_e32 v1, v1
	s_nop 0
	v_mul_f32_e32 v1, 0x4f7ffffe, v1
	v_cvt_u32_f32_e32 v1, v1
	v_mul_lo_u32 v4, v4, v1
	v_mul_hi_u32 v4, v1, v4
	v_add_u32_e32 v1, v1, v4
	s_waitcnt vmcnt(0)
	v_mul_hi_u32 v1, v3, v1
	v_mul_lo_u32 v4, v1, v2
	v_sub_u32_e32 v4, v3, v4
	v_add_u32_e32 v5, 1, v1
	v_cmp_ge_u32_e32 vcc, v4, v2
	v_add_u32_e32 v3, 1, v3
	s_nop 0
	v_cndmask_b32_e32 v1, v1, v5, vcc
	v_sub_u32_e32 v5, v4, v2
	v_cndmask_b32_e32 v4, v4, v5, vcc
	v_add_u32_e32 v5, 1, v1
	v_cmp_ge_u32_e32 vcc, v4, v2
	s_nop 1
	v_cndmask_b32_e32 v1, v1, v5, vcc
	v_mul_lo_u32 v4, v2, v1
	v_add_u32_e32 v2, v4, v2
	v_cmp_ne_u32_e32 vcc, v3, v2
	s_and_saveexec_b64 s[10:11], vcc
	s_xor_b64 s[22:23], exec, s[10:11]
	s_cbranch_execz .LBB0_513
	s_waitcnt lgkmcnt(0)
	v_add_u32_e32 v255, 1, v1
	v_mul_lo_u32 v255, v255, v0
	s_getpc_b64 s[100:101]
	s_add_u32 s100, s100, g_ctl@rel32@lo+13316
	s_addc_u32 s101, s101, g_ctl@rel32@hi+13324
	global_load_dword v0, v191, s[100:101] sc1
	s_waitcnt vmcnt(0)
	v_cmp_lt_u32_e32 vcc, v0, v255
	s_and_saveexec_b64 s[24:25], vcc
	s_cbranch_execz .LBB0_512
	s_mov_b32 s10, 1
	s_mov_b64 s[26:27], 0
	s_branch .LBB0_503

.LBB0_512:
	s_or_b64 exec, exec, s[24:25]
	s_waitcnt vmcnt(0)
	s_waitcnt vmcnt(0)

.LBB0_530:
	s_or_b64 exec, exec, s[22:23]
	s_waitcnt vmcnt(0)
	global_atomic_add v[188:189], v193, off
	s_waitcnt vmcnt(0)

.LBB0_839:
	buffer_inv sc1
	global_atomic_add v3, v[186:187], v193, off sc0
	v_cvt_f32_u32_e32 v1, v2
	v_sub_u32_e32 v4, 0, v2
	v_rcp_iflag_f32_e32 v1, v1
	s_nop 0
	v_mul_f32_e32 v1, 0x4f7ffffe, v1
	v_cvt_u32_f32_e32 v1, v1
	v_mul_lo_u32 v4, v4, v1
	v_mul_hi_u32 v4, v1, v4
	v_add_u32_e32 v1, v1, v4
	s_waitcnt vmcnt(0)
	v_mul_hi_u32 v1, v3, v1
	v_mul_lo_u32 v4, v1, v2
	v_sub_u32_e32 v4, v3, v4
	v_add_u32_e32 v5, 1, v1
	v_cmp_ge_u32_e32 vcc, v4, v2
	v_add_u32_e32 v3, 1, v3
	s_nop 0
	v_cndmask_b32_e32 v1, v1, v5, vcc
	v_sub_u32_e32 v5, v4, v2
	v_cndmask_b32_e32 v4, v4, v5, vcc
	v_add_u32_e32 v5, 1, v1
	v_cmp_ge_u32_e32 vcc, v4, v2
	s_nop 1
	v_cndmask_b32_e32 v1, v1, v5, vcc
	v_mul_lo_u32 v4, v2, v1
	v_add_u32_e32 v2, v4, v2
	v_cmp_ne_u32_e32 vcc, v3, v2
	s_and_saveexec_b64 s[2:3], vcc
	s_xor_b64 s[12:13], exec, s[2:3]
	s_cbranch_execz .LBB0_853
	s_waitcnt lgkmcnt(0)
	v_add_u32_e32 v255, 1, v1
	v_mul_lo_u32 v255, v255, v0
	s_getpc_b64 s[100:101]
	s_add_u32 s100, s100, g_ctl@rel32@lo+13316
	s_addc_u32 s101, s101, g_ctl@rel32@hi+13324
	global_load_dword v0, v191, s[100:101] sc1
	s_waitcnt vmcnt(0)
	v_cmp_lt_u32_e32 vcc, v0, v255
	s_and_saveexec_b64 s[14:15], vcc
	s_cbranch_execz .LBB0_852
	s_mov_b32 s20, 1
	s_mov_b64 s[16:17], 0
	s_branch .LBB0_843

.LBB0_852:
	s_or_b64 exec, exec, s[14:15]
	s_waitcnt vmcnt(0)
	s_waitcnt vmcnt(0)
